# S5 full scans: Y store addresses computed once per 32-step block and stepped by a per-direction +-2048 B pair (39 fewer VALU per block on the serial scan chain), on top of combo
# baseline (speedup 1.0000x reference)
.LBB0_947:
	v_mfma_f32_32x32x16_bf16 v[0:15], v[84:87], v[48:51], 0
	v_mfma_f32_32x32x16_bf16 v[32:47], v[84:87], v[56:59], 0
	v_mfma_f32_32x32x16_bf16 v[16:31], v[84:87], v[52:55], 0
	v_mfma_f32_32x32x16_bf16 v[144:159], v[84:87], v[60:63], 0
	s_nop 9
	v_permlane32_swap_b32_e32 v0, v32
	v_permlane32_swap_b32_e32 v1, v33
	v_permlane32_swap_b32_e32 v2, v34
	v_permlane32_swap_b32_e32 v3, v35
	v_permlane32_swap_b32_e32 v4, v36
	v_permlane32_swap_b32_e32 v5, v37
	v_permlane32_swap_b32_e32 v6, v38
	v_permlane32_swap_b32_e32 v7, v39
	v_permlane32_swap_b32_e32 v8, v40
	v_permlane32_swap_b32_e32 v9, v41
	v_permlane32_swap_b32_e32 v10, v42
	v_permlane32_swap_b32_e32 v11, v43
	v_permlane32_swap_b32_e32 v12, v44
	v_permlane32_swap_b32_e32 v13, v45
	v_permlane32_swap_b32_e32 v14, v46
	v_permlane32_swap_b32_e32 v15, v47
	v_permlane32_swap_b32_e32 v16, v144
	v_permlane32_swap_b32_e32 v17, v145
	v_permlane32_swap_b32_e32 v18, v146
	v_permlane32_swap_b32_e32 v19, v147
	v_permlane32_swap_b32_e32 v20, v148
	v_permlane32_swap_b32_e32 v21, v149
	v_permlane32_swap_b32_e32 v22, v150
	v_permlane32_swap_b32_e32 v23, v151
	v_permlane32_swap_b32_e32 v24, v152
	v_permlane32_swap_b32_e32 v25, v153
	v_permlane32_swap_b32_e32 v26, v154
	v_permlane32_swap_b32_e32 v27, v155
	v_permlane32_swap_b32_e32 v28, v156
	v_permlane32_swap_b32_e32 v29, v157
	v_permlane32_swap_b32_e32 v30, v158
	v_permlane32_swap_b32_e32 v31, v159
	v_fmac_f32_e32 v0, v106, v111
	v_fmac_f32_e32 v16, v107, v110
	v_fmac_f32_e32 v0, v108, v110
	v_fmac_f32_e32 v16, v109, v111
	v_cvt_pk_bf16_f32 v160, v0, v16
	ds_write_b32 v99, v160
	v_fmac_f32_e32 v1, v106, v16
	v_fmac_f32_e32 v17, v107, v0
	v_fmac_f32_e32 v1, v108, v0
	v_fmac_f32_e32 v17, v109, v16
	v_cvt_pk_bf16_f32 v161, v1, v17
	ds_write_b32 v99, v161 offset:528
	v_fmac_f32_e32 v2, v106, v17
	v_fmac_f32_e32 v18, v107, v1
	v_fmac_f32_e32 v2, v108, v1
	v_fmac_f32_e32 v18, v109, v17
	v_cvt_pk_bf16_f32 v162, v2, v18
	ds_write_b32 v99, v162 offset:1056
	v_fmac_f32_e32 v3, v106, v18
	v_fmac_f32_e32 v19, v107, v2
	v_fmac_f32_e32 v3, v108, v2
	v_fmac_f32_e32 v19, v109, v18
	v_cvt_pk_bf16_f32 v163, v3, v19
	ds_write_b32 v99, v163 offset:1584
	v_fmac_f32_e32 v32, v106, v19
	v_fmac_f32_e32 v144, v107, v3
	v_fmac_f32_e32 v32, v108, v3
	v_fmac_f32_e32 v144, v109, v19
	v_cvt_pk_bf16_f32 v160, v32, v144
	ds_write_b32 v99, v160 offset:2112
	v_fmac_f32_e32 v33, v106, v144
	v_fmac_f32_e32 v145, v107, v32
	v_fmac_f32_e32 v33, v108, v32
	v_fmac_f32_e32 v145, v109, v144
	v_cvt_pk_bf16_f32 v161, v33, v145
	ds_write_b32 v99, v161 offset:2640
	v_fmac_f32_e32 v34, v106, v145
	v_fmac_f32_e32 v146, v107, v33
	v_fmac_f32_e32 v34, v108, v33
	v_fmac_f32_e32 v146, v109, v145
	v_cvt_pk_bf16_f32 v162, v34, v146
	ds_write_b32 v99, v162 offset:3168
	v_fmac_f32_e32 v35, v106, v146
	v_fmac_f32_e32 v147, v107, v34
	v_fmac_f32_e32 v35, v108, v34
	v_fmac_f32_e32 v147, v109, v146
	v_cvt_pk_bf16_f32 v163, v35, v147
	ds_write_b32 v99, v163 offset:3696
	v_fmac_f32_e32 v4, v106, v147
	v_fmac_f32_e32 v20, v107, v35
	v_fmac_f32_e32 v4, v108, v35
	v_fmac_f32_e32 v20, v109, v147
	v_cvt_pk_bf16_f32 v160, v4, v20
	ds_write_b32 v99, v160 offset:4224
	v_fmac_f32_e32 v5, v106, v20
	v_fmac_f32_e32 v21, v107, v4
	v_fmac_f32_e32 v5, v108, v4
	v_fmac_f32_e32 v21, v109, v20
	v_cvt_pk_bf16_f32 v161, v5, v21
	ds_write_b32 v99, v161 offset:4752
	v_fmac_f32_e32 v6, v106, v21
	v_fmac_f32_e32 v22, v107, v5
	v_fmac_f32_e32 v6, v108, v5
	v_fmac_f32_e32 v22, v109, v21
	v_cvt_pk_bf16_f32 v162, v6, v22
	ds_write_b32 v99, v162 offset:5280
	v_fmac_f32_e32 v7, v106, v22
	v_fmac_f32_e32 v23, v107, v6
	v_fmac_f32_e32 v7, v108, v6
	v_fmac_f32_e32 v23, v109, v22
	v_cvt_pk_bf16_f32 v163, v7, v23
	ds_write_b32 v99, v163 offset:5808
	v_fmac_f32_e32 v36, v106, v23
	v_fmac_f32_e32 v148, v107, v7
	v_fmac_f32_e32 v36, v108, v7
	v_fmac_f32_e32 v148, v109, v23
	v_cvt_pk_bf16_f32 v160, v36, v148
	ds_write_b32 v99, v160 offset:6336
	v_fmac_f32_e32 v37, v106, v148
	v_fmac_f32_e32 v149, v107, v36
	v_fmac_f32_e32 v37, v108, v36
	v_fmac_f32_e32 v149, v109, v148
	v_cvt_pk_bf16_f32 v161, v37, v149
	ds_write_b32 v99, v161 offset:6864
	v_fmac_f32_e32 v38, v106, v149
	v_fmac_f32_e32 v150, v107, v37
	v_fmac_f32_e32 v38, v108, v37
	v_fmac_f32_e32 v150, v109, v149
	v_cvt_pk_bf16_f32 v162, v38, v150
	ds_write_b32 v99, v162 offset:7392
	v_fmac_f32_e32 v39, v106, v150
	v_fmac_f32_e32 v151, v107, v38
	v_fmac_f32_e32 v39, v108, v38
	v_fmac_f32_e32 v151, v109, v150
	v_cvt_pk_bf16_f32 v163, v39, v151
	ds_write_b32 v99, v163 offset:7920
	v_fmac_f32_e32 v8, v106, v151
	v_fmac_f32_e32 v24, v107, v39
	v_fmac_f32_e32 v8, v108, v39
	v_fmac_f32_e32 v24, v109, v151
	v_cvt_pk_bf16_f32 v160, v8, v24
	ds_write_b32 v99, v160 offset:8448
	v_fmac_f32_e32 v9, v106, v24
	v_fmac_f32_e32 v25, v107, v8
	v_fmac_f32_e32 v9, v108, v8
	v_fmac_f32_e32 v25, v109, v24
	v_cvt_pk_bf16_f32 v161, v9, v25
	ds_write_b32 v99, v161 offset:8976
	v_fmac_f32_e32 v10, v106, v25
	v_fmac_f32_e32 v26, v107, v9
	v_fmac_f32_e32 v10, v108, v9
	v_fmac_f32_e32 v26, v109, v25
	v_cvt_pk_bf16_f32 v162, v10, v26
	ds_write_b32 v99, v162 offset:9504
	v_fmac_f32_e32 v11, v106, v26
	v_fmac_f32_e32 v27, v107, v10
	v_fmac_f32_e32 v11, v108, v10
	v_fmac_f32_e32 v27, v109, v26
	v_cvt_pk_bf16_f32 v163, v11, v27
	ds_write_b32 v99, v163 offset:10032
	v_fmac_f32_e32 v40, v106, v27
	v_fmac_f32_e32 v152, v107, v11
	v_fmac_f32_e32 v40, v108, v11
	v_fmac_f32_e32 v152, v109, v27
	v_cvt_pk_bf16_f32 v160, v40, v152
	ds_write_b32 v99, v160 offset:10560
	v_fmac_f32_e32 v41, v106, v152
	v_fmac_f32_e32 v153, v107, v40
	v_fmac_f32_e32 v41, v108, v40
	v_fmac_f32_e32 v153, v109, v152
	v_cvt_pk_bf16_f32 v161, v41, v153
	ds_write_b32 v99, v161 offset:11088
	v_fmac_f32_e32 v42, v106, v153
	v_fmac_f32_e32 v154, v107, v41
	v_fmac_f32_e32 v42, v108, v41
	v_fmac_f32_e32 v154, v109, v153
	v_cvt_pk_bf16_f32 v162, v42, v154
	ds_write_b32 v99, v162 offset:11616
	v_fmac_f32_e32 v43, v106, v154
	v_fmac_f32_e32 v155, v107, v42
	v_fmac_f32_e32 v43, v108, v42
	v_fmac_f32_e32 v155, v109, v154
	v_cvt_pk_bf16_f32 v163, v43, v155
	ds_write_b32 v99, v163 offset:12144
	v_fmac_f32_e32 v12, v106, v155
	v_fmac_f32_e32 v28, v107, v43
	v_fmac_f32_e32 v12, v108, v43
	v_fmac_f32_e32 v28, v109, v155
	v_cvt_pk_bf16_f32 v160, v12, v28
	ds_write_b32 v99, v160 offset:12672
	v_fmac_f32_e32 v13, v106, v28
	v_fmac_f32_e32 v29, v107, v12
	v_fmac_f32_e32 v13, v108, v12
	v_fmac_f32_e32 v29, v109, v28
	v_cvt_pk_bf16_f32 v161, v13, v29
	ds_write_b32 v99, v161 offset:13200
	v_fmac_f32_e32 v14, v106, v29
	v_fmac_f32_e32 v30, v107, v13
	v_fmac_f32_e32 v14, v108, v13
	v_fmac_f32_e32 v30, v109, v29
	v_cvt_pk_bf16_f32 v162, v14, v30
	ds_write_b32 v99, v162 offset:13728
	v_fmac_f32_e32 v15, v106, v30
	v_fmac_f32_e32 v31, v107, v14
	v_fmac_f32_e32 v15, v108, v14
	v_fmac_f32_e32 v31, v109, v30
	v_cvt_pk_bf16_f32 v163, v15, v31
	ds_write_b32 v99, v163 offset:14256
	v_fmac_f32_e32 v44, v106, v31
	v_fmac_f32_e32 v156, v107, v15
	v_fmac_f32_e32 v44, v108, v15
	v_fmac_f32_e32 v156, v109, v31
	v_cvt_pk_bf16_f32 v160, v44, v156
	ds_write_b32 v99, v160 offset:14784
	v_fmac_f32_e32 v45, v106, v156
	v_fmac_f32_e32 v157, v107, v44
	v_fmac_f32_e32 v45, v108, v44
	v_fmac_f32_e32 v157, v109, v156
	v_cvt_pk_bf16_f32 v161, v45, v157
	ds_write_b32 v99, v161 offset:15312
	v_fmac_f32_e32 v46, v106, v157
	v_fmac_f32_e32 v158, v107, v45
	v_fmac_f32_e32 v46, v108, v45
	v_fmac_f32_e32 v158, v109, v157
	v_cvt_pk_bf16_f32 v162, v46, v158
	ds_write_b32 v99, v162 offset:15840
	v_fmac_f32_e32 v47, v106, v158
	v_fmac_f32_e32 v159, v107, v46
	v_fmac_f32_e32 v47, v108, v46
	v_fmac_f32_e32 v159, v109, v158
	v_cvt_pk_bf16_f32 v163, v47, v159
	ds_write_b32 v99, v163 offset:16368
	v_mov_b32_e32 v110, v47
	v_mov_b32_e32 v111, v159
	s_waitcnt lgkmcnt(0)
	ds_read_b128 v[0:3], v119
	ds_read_b128 v[4:7], v119 offset:64
	v_lshl_add_u32 v8, s14, 5, v96
	s_add_i32 s14, s14, 1
	s_waitcnt vmcnt(0)
	v_mov_b64_e32 v[86:87], v[82:83]
	s_cmp_lg_u32 s14, 8
	v_mov_b64_e32 v[84:85], v[80:81]
	s_waitcnt lgkmcnt(1)
	v_mfma_f32_16x16x32_bf16 v[0:3], v[0:3], v[64:67], 0
	s_waitcnt lgkmcnt(0)
	v_mfma_f32_16x16x32_bf16 v[0:3], v[4:7], v[68:71], v[0:3]
	ds_read_b128 v[4:7], v119 offset:128
	s_waitcnt lgkmcnt(0)
	v_mfma_f32_16x16x32_bf16 v[0:3], v[4:7], v[72:75], v[0:3]
	ds_read_b128 v[4:7], v119 offset:192
	s_waitcnt lgkmcnt(0)
	v_mfma_f32_16x16x32_bf16 v[0:3], v[4:7], v[76:79], v[0:3]
	v_sub_u32_e32 v4, 0xff, v8
	v_cndmask_b32_e64 v4, v4, v8, s[8:9]
	v_add_u32_e32 v4, s10, v4
	v_ashrrev_i32_e32 v5, 31, v4
	v_lshlrev_b64 v[4:5], 11, v[4:5]
	v_lshl_add_u64 v[4:5], v[114:115], 0, v[4:5]
	v_mov_b32_e32 v10, 0x800
	v_sub_u32_e32 v11, 0, v10
	v_cndmask_b32_e64 v10, v11, v10, s[8:9]
	v_ashrrev_i32_e32 v11, 31, v10
	global_store_dword v[4:5], v0, off
	v_lshl_add_u64 v[6:7], v[4:5], 0, v[10:11]
	global_store_dword v[6:7], v1, off
	v_lshl_add_u64 v[6:7], v[6:7], 0, v[10:11]
	global_store_dword v[6:7], v2, off
	v_lshl_add_u64 v[6:7], v[6:7], 0, v[10:11]
	global_store_dword v[6:7], v3, off
	v_lshl_add_u64 v[12:13], v[10:11], 4, v[4:5]
	ds_read_b128 v[0:3], v119 offset:8448
	ds_read_b128 v[4:7], v119 offset:8512
	s_waitcnt lgkmcnt(1)
	v_mfma_f32_16x16x32_bf16 v[0:3], v[0:3], v[64:67], 0
	s_waitcnt lgkmcnt(0)
	v_mfma_f32_16x16x32_bf16 v[0:3], v[4:7], v[68:71], v[0:3]
	ds_read_b128 v[4:7], v119 offset:8576
	s_waitcnt lgkmcnt(0)
	v_mfma_f32_16x16x32_bf16 v[0:3], v[4:7], v[72:75], v[0:3]
	ds_read_b128 v[4:7], v119 offset:8640
	s_waitcnt lgkmcnt(0)
	v_mfma_f32_16x16x32_bf16 v[0:3], v[4:7], v[76:79], v[0:3]
	v_lshl_add_u64 v[14:15], v[12:13], 0, v[10:11]
	v_lshl_add_u64 v[16:17], v[14:15], 0, v[10:11]
	v_lshl_add_u64 v[18:19], v[16:17], 0, v[10:11]
	s_nop 4
	global_store_dword v[12:13], v0, off
	global_store_dword v[14:15], v1, off
	global_store_dword v[16:17], v2, off
	global_store_dword v[18:19], v3, off
	s_waitcnt lgkmcnt(0)
	s_cbranch_scc1 .LBB0_945
	s_ashr_i32 s13, s12, 31
	s_lshl_b64 s[14:15], s[12:13], 13
	s_or_b64 s[14:15], s[14:15], s[84:85]
	s_add_u32 s14, s14, s96
	s_addc_u32 s15, s15, 0
	v_lshl_add_u64 v[0:1], s[14:15], 0, v[88:89]
	s_load_dwordx2 s[14:15], s[4:5], 0x100
	s_waitcnt lgkmcnt(0)
	v_lshlrev_b64 v[0:1], 2, v[0:1]
	v_lshl_add_u64 v[2:3], s[14:15], 0, v[0:1]
	s_brev_b32 s14, 32
	v_add_co_u32_e32 v2, vcc, s14, v2
	s_addk_i32 s10, 0x2000
	s_nop 0
	v_addc_co_u32_e32 v3, vcc, 0, v3, vcc
	global_store_dword v[2:3], v110, off
	s_load_dwordx2 s[14:15], s[4:5], 0x100
	s_waitcnt lgkmcnt(0)
	s_lshl_b32 s96, s11, 1
	v_lshl_add_u64 v[0:1], s[14:15], 0, v[0:1]
	s_mov_b32 s14, 0x4100000
	v_add_co_u32_e32 v0, vcc, s14, v0
	v_mov_b32_e32 v72, 0
	s_nop 0
	v_addc_co_u32_e32 v1, vcc, 0, v1, vcc
	global_store_dword v[0:1], v111, off
	v_or_b32_e32 v0, s10, v117
	v_ashrrev_i32_e32 v1, 31, v0
	v_lshlrev_b64 v[0:1], 12, v[0:1]
	v_lshl_add_u64 v[0:1], s[24:25], 0, v[0:1]
	v_lshl_add_u64 v[0:1], v[0:1], 0, s[96:97]
	v_lshl_add_u64 v[0:1], v[92:93], 1, v[0:1]
	global_load_dwordx4 v[68:71], v[0:1], off
	s_mov_b32 s11, 0
	v_mov_b32_e32 v73, v72
	s_waitcnt vmcnt(0)
	v_mov_b64_e32 v[64:65], v[68:69]
	v_mov_b64_e32 v[66:67], v[70:71]

.LBB0_1057:
	v_mfma_f32_32x32x16_bf16 v[0:15], v[84:87], v[72:75], 0
	v_mfma_f32_32x32x16_bf16 v[32:47], v[84:87], v[48:51], 0
	v_mfma_f32_32x32x16_bf16 v[16:31], v[84:87], v[76:79], 0
	v_mfma_f32_32x32x16_bf16 v[144:159], v[84:87], v[52:55], 0
	s_nop 9
	v_permlane32_swap_b32_e32 v0, v32
	v_permlane32_swap_b32_e32 v1, v33
	v_permlane32_swap_b32_e32 v2, v34
	v_permlane32_swap_b32_e32 v3, v35
	v_permlane32_swap_b32_e32 v4, v36
	v_permlane32_swap_b32_e32 v5, v37
	v_permlane32_swap_b32_e32 v6, v38
	v_permlane32_swap_b32_e32 v7, v39
	v_permlane32_swap_b32_e32 v8, v40
	v_permlane32_swap_b32_e32 v9, v41
	v_permlane32_swap_b32_e32 v10, v42
	v_permlane32_swap_b32_e32 v11, v43
	v_permlane32_swap_b32_e32 v12, v44
	v_permlane32_swap_b32_e32 v13, v45
	v_permlane32_swap_b32_e32 v14, v46
	v_permlane32_swap_b32_e32 v15, v47
	v_permlane32_swap_b32_e32 v16, v144
	v_permlane32_swap_b32_e32 v17, v145
	v_permlane32_swap_b32_e32 v18, v146
	v_permlane32_swap_b32_e32 v19, v147
	v_permlane32_swap_b32_e32 v20, v148
	v_permlane32_swap_b32_e32 v21, v149
	v_permlane32_swap_b32_e32 v22, v150
	v_permlane32_swap_b32_e32 v23, v151
	v_permlane32_swap_b32_e32 v24, v152
	v_permlane32_swap_b32_e32 v25, v153
	v_permlane32_swap_b32_e32 v26, v154
	v_permlane32_swap_b32_e32 v27, v155
	v_permlane32_swap_b32_e32 v28, v156
	v_permlane32_swap_b32_e32 v29, v157
	v_permlane32_swap_b32_e32 v30, v158
	v_permlane32_swap_b32_e32 v31, v159
	v_fmac_f32_e32 v0, v108, v107
	v_fmac_f32_e32 v16, v109, v106
	v_fmac_f32_e32 v0, v114, v106
	v_fmac_f32_e32 v16, v115, v107
	v_cvt_pk_bf16_f32 v160, v0, v16
	ds_write_b32 v101, v160
	v_fmac_f32_e32 v1, v108, v16
	v_fmac_f32_e32 v17, v109, v0
	v_fmac_f32_e32 v1, v114, v0
	v_fmac_f32_e32 v17, v115, v16
	v_cvt_pk_bf16_f32 v161, v1, v17
	ds_write_b32 v101, v161 offset:528
	v_fmac_f32_e32 v2, v108, v17
	v_fmac_f32_e32 v18, v109, v1
	v_fmac_f32_e32 v2, v114, v1
	v_fmac_f32_e32 v18, v115, v17
	v_cvt_pk_bf16_f32 v162, v2, v18
	ds_write_b32 v101, v162 offset:1056
	v_fmac_f32_e32 v3, v108, v18
	v_fmac_f32_e32 v19, v109, v2
	v_fmac_f32_e32 v3, v114, v2
	v_fmac_f32_e32 v19, v115, v18
	v_cvt_pk_bf16_f32 v163, v3, v19
	ds_write_b32 v101, v163 offset:1584
	v_fmac_f32_e32 v32, v108, v19
	v_fmac_f32_e32 v144, v109, v3
	v_fmac_f32_e32 v32, v114, v3
	v_fmac_f32_e32 v144, v115, v19
	v_cvt_pk_bf16_f32 v160, v32, v144
	ds_write_b32 v101, v160 offset:2112
	v_fmac_f32_e32 v33, v108, v144
	v_fmac_f32_e32 v145, v109, v32
	v_fmac_f32_e32 v33, v114, v32
	v_fmac_f32_e32 v145, v115, v144
	v_cvt_pk_bf16_f32 v161, v33, v145
	ds_write_b32 v101, v161 offset:2640
	v_fmac_f32_e32 v34, v108, v145
	v_fmac_f32_e32 v146, v109, v33
	v_fmac_f32_e32 v34, v114, v33
	v_fmac_f32_e32 v146, v115, v145
	v_cvt_pk_bf16_f32 v162, v34, v146
	ds_write_b32 v101, v162 offset:3168
	v_fmac_f32_e32 v35, v108, v146
	v_fmac_f32_e32 v147, v109, v34
	v_fmac_f32_e32 v35, v114, v34
	v_fmac_f32_e32 v147, v115, v146
	v_cvt_pk_bf16_f32 v163, v35, v147
	ds_write_b32 v101, v163 offset:3696
	v_fmac_f32_e32 v4, v108, v147
	v_fmac_f32_e32 v20, v109, v35
	v_fmac_f32_e32 v4, v114, v35
	v_fmac_f32_e32 v20, v115, v147
	v_cvt_pk_bf16_f32 v160, v4, v20
	ds_write_b32 v101, v160 offset:4224
	v_fmac_f32_e32 v5, v108, v20
	v_fmac_f32_e32 v21, v109, v4
	v_fmac_f32_e32 v5, v114, v4
	v_fmac_f32_e32 v21, v115, v20
	v_cvt_pk_bf16_f32 v161, v5, v21
	ds_write_b32 v101, v161 offset:4752
	v_fmac_f32_e32 v6, v108, v21
	v_fmac_f32_e32 v22, v109, v5
	v_fmac_f32_e32 v6, v114, v5
	v_fmac_f32_e32 v22, v115, v21
	v_cvt_pk_bf16_f32 v162, v6, v22
	ds_write_b32 v101, v162 offset:5280
	v_fmac_f32_e32 v7, v108, v22
	v_fmac_f32_e32 v23, v109, v6
	v_fmac_f32_e32 v7, v114, v6
	v_fmac_f32_e32 v23, v115, v22
	v_cvt_pk_bf16_f32 v163, v7, v23
	ds_write_b32 v101, v163 offset:5808
	v_fmac_f32_e32 v36, v108, v23
	v_fmac_f32_e32 v148, v109, v7
	v_fmac_f32_e32 v36, v114, v7
	v_fmac_f32_e32 v148, v115, v23
	v_cvt_pk_bf16_f32 v160, v36, v148
	ds_write_b32 v101, v160 offset:6336
	v_fmac_f32_e32 v37, v108, v148
	v_fmac_f32_e32 v149, v109, v36
	v_fmac_f32_e32 v37, v114, v36
	v_fmac_f32_e32 v149, v115, v148
	v_cvt_pk_bf16_f32 v161, v37, v149
	ds_write_b32 v101, v161 offset:6864
	v_fmac_f32_e32 v38, v108, v149
	v_fmac_f32_e32 v150, v109, v37
	v_fmac_f32_e32 v38, v114, v37
	v_fmac_f32_e32 v150, v115, v149
	v_cvt_pk_bf16_f32 v162, v38, v150
	ds_write_b32 v101, v162 offset:7392
	v_fmac_f32_e32 v39, v108, v150
	v_fmac_f32_e32 v151, v109, v38
	v_fmac_f32_e32 v39, v114, v38
	v_fmac_f32_e32 v151, v115, v150
	v_cvt_pk_bf16_f32 v163, v39, v151
	ds_write_b32 v101, v163 offset:7920
	v_fmac_f32_e32 v8, v108, v151
	v_fmac_f32_e32 v24, v109, v39
	v_fmac_f32_e32 v8, v114, v39
	v_fmac_f32_e32 v24, v115, v151
	v_cvt_pk_bf16_f32 v160, v8, v24
	ds_write_b32 v101, v160 offset:8448
	v_fmac_f32_e32 v9, v108, v24
	v_fmac_f32_e32 v25, v109, v8
	v_fmac_f32_e32 v9, v114, v8
	v_fmac_f32_e32 v25, v115, v24
	v_cvt_pk_bf16_f32 v161, v9, v25
	ds_write_b32 v101, v161 offset:8976
	v_fmac_f32_e32 v10, v108, v25
	v_fmac_f32_e32 v26, v109, v9
	v_fmac_f32_e32 v10, v114, v9
	v_fmac_f32_e32 v26, v115, v25
	v_cvt_pk_bf16_f32 v162, v10, v26
	ds_write_b32 v101, v162 offset:9504
	v_fmac_f32_e32 v11, v108, v26
	v_fmac_f32_e32 v27, v109, v10
	v_fmac_f32_e32 v11, v114, v10
	v_fmac_f32_e32 v27, v115, v26
	v_cvt_pk_bf16_f32 v163, v11, v27
	ds_write_b32 v101, v163 offset:10032
	v_fmac_f32_e32 v40, v108, v27
	v_fmac_f32_e32 v152, v109, v11
	v_fmac_f32_e32 v40, v114, v11
	v_fmac_f32_e32 v152, v115, v27
	v_cvt_pk_bf16_f32 v160, v40, v152
	ds_write_b32 v101, v160 offset:10560
	v_fmac_f32_e32 v41, v108, v152
	v_fmac_f32_e32 v153, v109, v40
	v_fmac_f32_e32 v41, v114, v40
	v_fmac_f32_e32 v153, v115, v152
	v_cvt_pk_bf16_f32 v161, v41, v153
	ds_write_b32 v101, v161 offset:11088
	v_fmac_f32_e32 v42, v108, v153
	v_fmac_f32_e32 v154, v109, v41
	v_fmac_f32_e32 v42, v114, v41
	v_fmac_f32_e32 v154, v115, v153
	v_cvt_pk_bf16_f32 v162, v42, v154
	ds_write_b32 v101, v162 offset:11616
	v_fmac_f32_e32 v43, v108, v154
	v_fmac_f32_e32 v155, v109, v42
	v_fmac_f32_e32 v43, v114, v42
	v_fmac_f32_e32 v155, v115, v154
	v_cvt_pk_bf16_f32 v163, v43, v155
	ds_write_b32 v101, v163 offset:12144
	v_fmac_f32_e32 v12, v108, v155
	v_fmac_f32_e32 v28, v109, v43
	v_fmac_f32_e32 v12, v114, v43
	v_fmac_f32_e32 v28, v115, v155
	v_cvt_pk_bf16_f32 v160, v12, v28
	ds_write_b32 v101, v160 offset:12672
	v_fmac_f32_e32 v13, v108, v28
	v_fmac_f32_e32 v29, v109, v12
	v_fmac_f32_e32 v13, v114, v12
	v_fmac_f32_e32 v29, v115, v28
	v_cvt_pk_bf16_f32 v161, v13, v29
	ds_write_b32 v101, v161 offset:13200
	v_fmac_f32_e32 v14, v108, v29
	v_fmac_f32_e32 v30, v109, v13
	v_fmac_f32_e32 v14, v114, v13
	v_fmac_f32_e32 v30, v115, v29
	v_cvt_pk_bf16_f32 v162, v14, v30
	ds_write_b32 v101, v162 offset:13728
	v_fmac_f32_e32 v15, v108, v30
	v_fmac_f32_e32 v31, v109, v14
	v_fmac_f32_e32 v15, v114, v14
	v_fmac_f32_e32 v31, v115, v30
	v_cvt_pk_bf16_f32 v163, v15, v31
	ds_write_b32 v101, v163 offset:14256
	v_fmac_f32_e32 v44, v108, v31
	v_fmac_f32_e32 v156, v109, v15
	v_fmac_f32_e32 v44, v114, v15
	v_fmac_f32_e32 v156, v115, v31
	v_cvt_pk_bf16_f32 v160, v44, v156
	ds_write_b32 v101, v160 offset:14784
	v_fmac_f32_e32 v45, v108, v156
	v_fmac_f32_e32 v157, v109, v44
	v_fmac_f32_e32 v45, v114, v44
	v_fmac_f32_e32 v157, v115, v156
	v_cvt_pk_bf16_f32 v161, v45, v157
	ds_write_b32 v101, v161 offset:15312
	v_fmac_f32_e32 v46, v108, v157
	v_fmac_f32_e32 v158, v109, v45
	v_fmac_f32_e32 v46, v114, v45
	v_fmac_f32_e32 v158, v115, v157
	v_cvt_pk_bf16_f32 v162, v46, v158
	ds_write_b32 v101, v162 offset:15840
	v_fmac_f32_e32 v47, v108, v158
	v_fmac_f32_e32 v159, v109, v46
	v_fmac_f32_e32 v47, v114, v46
	v_fmac_f32_e32 v159, v115, v158
	v_cvt_pk_bf16_f32 v163, v47, v159
	ds_write_b32 v101, v163 offset:16368
	v_mov_b32_e32 v106, v47
	v_mov_b32_e32 v107, v159
	s_waitcnt lgkmcnt(0)
	ds_read_b128 v[0:3], v124
	ds_read_b128 v[4:7], v124 offset:64
	v_lshl_add_u32 v8, s14, 5, v98
	s_add_i32 s14, s14, 1
	s_waitcnt vmcnt(0)
	v_mov_b64_e32 v[86:87], v[82:83]
	s_cmp_lg_u32 s14, 8
	v_mov_b64_e32 v[84:85], v[80:81]
	s_waitcnt lgkmcnt(1)
	v_mfma_f32_16x16x32_bf16 v[0:3], v[0:3], v[56:59], 0
	s_waitcnt lgkmcnt(0)
	v_mfma_f32_16x16x32_bf16 v[0:3], v[4:7], v[60:63], v[0:3]
	ds_read_b128 v[4:7], v124 offset:128
	s_waitcnt lgkmcnt(0)
	v_mfma_f32_16x16x32_bf16 v[0:3], v[4:7], v[64:67], v[0:3]
	ds_read_b128 v[4:7], v124 offset:192
	s_waitcnt lgkmcnt(0)
	v_mfma_f32_16x16x32_bf16 v[0:3], v[4:7], v[68:71], v[0:3]
	v_sub_u32_e32 v4, 0xff, v8
	v_cndmask_b32_e64 v4, v4, v8, s[8:9]
	v_add_u32_e32 v4, s13, v4
	v_ashrrev_i32_e32 v5, 31, v4
	v_lshlrev_b64 v[4:5], 11, v[4:5]
	v_lshl_add_u64 v[4:5], v[112:113], 0, v[4:5]
	v_mov_b32_e32 v10, 0x800
	v_sub_u32_e32 v11, 0, v10
	v_cndmask_b32_e64 v10, v11, v10, s[8:9]
	v_ashrrev_i32_e32 v11, 31, v10
	global_store_dword v[4:5], v0, off
	v_lshl_add_u64 v[6:7], v[4:5], 0, v[10:11]
	global_store_dword v[6:7], v1, off
	v_lshl_add_u64 v[6:7], v[6:7], 0, v[10:11]
	global_store_dword v[6:7], v2, off
	v_lshl_add_u64 v[6:7], v[6:7], 0, v[10:11]
	global_store_dword v[6:7], v3, off
	v_lshl_add_u64 v[12:13], v[10:11], 4, v[4:5]
	ds_read_b128 v[0:3], v124 offset:8448
	ds_read_b128 v[4:7], v124 offset:8512
	s_waitcnt lgkmcnt(1)
	v_mfma_f32_16x16x32_bf16 v[0:3], v[0:3], v[56:59], 0
	s_waitcnt lgkmcnt(0)
	v_mfma_f32_16x16x32_bf16 v[0:3], v[4:7], v[60:63], v[0:3]
	ds_read_b128 v[4:7], v124 offset:8576
	s_waitcnt lgkmcnt(0)
	v_mfma_f32_16x16x32_bf16 v[0:3], v[4:7], v[64:67], v[0:3]
	ds_read_b128 v[4:7], v124 offset:8640
	s_waitcnt lgkmcnt(0)
	v_mfma_f32_16x16x32_bf16 v[0:3], v[4:7], v[68:71], v[0:3]
	v_lshl_add_u64 v[14:15], v[12:13], 0, v[10:11]
	v_lshl_add_u64 v[16:17], v[14:15], 0, v[10:11]
	v_lshl_add_u64 v[18:19], v[16:17], 0, v[10:11]
	s_nop 4
	global_store_dword v[12:13], v0, off
	global_store_dword v[14:15], v1, off
	global_store_dword v[16:17], v2, off
	global_store_dword v[18:19], v3, off
	s_waitcnt lgkmcnt(0)
	s_cbranch_scc1 .LBB0_1055
	s_and_b64 vcc, exec, s[10:11]
	s_cbranch_vccnz .LBB0_1062
	s_ashr_i32 s13, s12, 31
	s_lshl_b64 s[10:11], s[12:13], 13
	s_or_b64 s[10:11], s[10:11], s[80:81]
	s_add_u32 s10, s10, s96
	s_addc_u32 s11, s11, 0
	v_lshl_add_u64 v[0:1], s[10:11], 0, v[88:89]
	v_lshlrev_b64 v[0:1], 2, v[0:1]
	s_load_dwordx2 s[10:11], s[4:5], 0x100
	s_waitcnt lgkmcnt(0)
	s_nop 0
	v_lshl_add_u64 v[2:3], s[10:11], 0, v[0:1]
	v_add_co_u32_e32 v2, vcc, 0x4000000, v2
	s_nop 1
	v_addc_co_u32_e32 v3, vcc, 0, v3, vcc
	global_store_dword v[2:3], v106, off
	s_load_dwordx2 s[10:11], s[4:5], 0x100
	s_waitcnt lgkmcnt(0)
	s_nop 0
	v_lshl_add_u64 v[0:1], s[10:11], 0, v[0:1]
	v_add_co_u32_e32 v0, vcc, 0x4100000, v0
	s_nop 1
	v_addc_co_u32_e32 v1, vcc, 0, v1, vcc
	global_store_dword v[0:1], v107, off
